# ph_post head-norm/rotary part rewritten by hand: one (token, 8-head group) per trip with the next token's loads in flight, branch-free lane roles via exec masks
# speedup vs baseline: 1.0419x; 1.0122x over previous
.LBB0_690:
	s_mov_b32 s56, 0x800000
	s_or_b64 exec, exec, s[4:5]
	s_mov_b64 s[4:5], s[66:67]
	v_mov_b32_e32 v0, v1
	s_waitcnt lgkmcnt(0)
	s_barrier
	s_load_dwordx4 s[48:51], s[4:5], 0xf8
	s_load_dwordx4 s[8:11], s[4:5], 0x80
	v_mbcnt_lo_u32_b32 v0, -1, v0
	v_mbcnt_hi_u32_b32 v0, -1, v0
	v_add_u32_e32 v2, s86, v0
	v_and_b32_e32 v58, 63, v0
	v_readfirstlane_b32 s0, v2
	s_nop 1
	v_writelane_b32 v255, s0, 36
	s_ashr_i32 s0, s0, 6
	s_add_i32 s1, s0, s55
	v_writelane_b32 v255, s0, 37
	s_waitcnt lgkmcnt(0)
	s_add_u32 s46, s50, 0x6c00000
	s_addc_u32 s47, s51, 0
	v_writelane_b32 v255, s8, 38
	s_add_u32 s58, s50, 0xd800000
	s_addc_u32 s59, s51, 0
	v_writelane_b32 v255, s9, 39
	v_writelane_b32 v255, s10, 40
	v_writelane_b32 v255, s11, 41
	s_cmpk_gt_i32 s1, 0x3fff
	s_cbranch_scc1 .LBB0_826
	s_load_dwordx4 s[24:27], s[66:67], 0xc8
	s_load_dwordx4 s[28:31], s[66:67], 0xe0
	v_readlane_b32 s5, v255, 21
	s_and_b32 s2, s1, 3
	s_lshr_b32 s3, s1, 2
	s_lshr_b32 s4, s68, 2
	s_mov_b32 s16, 0x3c800000
	v_lshrrev_b32_e32 v23, 3, v58
	s_lshl_b32 s0, s2, 3
	v_add_u32_e32 v23, s0, v23
	v_and_b32_e32 v59, 7, v58
	v_add_u32_e32 v66, -20, v23
	v_cmp_gt_u32_e64 s[6:7], 8, v66
	s_nop 1
	v_add_u32_e32 v66, -12, v23
	v_cmp_gt_u32_e64 s[8:9], 6, v66
	s_nop 1
	v_add_u32_e32 v66, -26, v23
	v_cmp_gt_u32_e64 s[10:11], 2, v66
	s_nop 1
	v_add_u32_e32 v66, -28, v23
	v_cmp_gt_u32_e64 s[12:13], 4, v66
	s_nop 1
	s_nop 3
	s_or_b64 s[10:11], s[8:9], s[10:11]
	s_or_b64 s[8:9], s[10:11], s[12:13]
	s_not_b64 s[8:9], s[8:9]
	s_mov_b64 s[12:13], s[8:9]
	v_add_u32_e32 v66, -6, v23
	v_cmp_gt_u32_e64 s[14:15], 6, v66
	s_nop 1
	v_add_u32_e32 v66, -24, v23
	v_cmp_gt_u32_e64 s[20:21], 2, v66
	s_nop 1
	s_nop 3
	s_or_b64 s[14:15], s[14:15], s[20:21]
	s_or_b64 s[10:11], s[10:11], s[14:15]
	v_add_u32_e32 v66, -18, v23
	v_cmp_gt_u32_e64 s[14:15], 8, v66
	s_nop 1
	s_nop 3
	v_mov_b32_e32 v17, 1.0
	v_cmp_gt_u32_e32 vcc, 6, v23
	s_nop 1
	v_mov_b32_e32 v67, 0x3e000000
	v_cndmask_b32_e32 v17, v17, v67, vcc
	v_add_u32_e32 v66, -18, v23
	v_cmp_gt_u32_e32 vcc, 6, v66
	s_nop 1
	v_mov_b32_e32 v67, 0x3e000000
	v_cndmask_b32_e32 v17, v17, v67, vcc
	v_and_b32_e32 v66, 2, v59
	v_cmp_eq_u32_e32 vcc, 0, v66
	s_nop 1
	v_mov_b32_e32 v67, 0x80000000
	v_cndmask_b32_e32 v22, 0, v67, vcc
	v_and_b32_e32 v66, 1, v59
	v_lshlrev_b32_e32 v21, 6, v66
	v_and_b32_e32 v66, 4, v59
	v_lshl_add_u32 v21, v66, 5, v21
	v_lshlrev_b32_e32 v65, 4, v59
	v_mov_b32_e32 v0, 0
	v_mov_b32_e32 v64, 0
	v_cmp_gt_u32_e32 vcc, 20, v23
	s_nop 1
	s_mov_b32 s0, 0x6c00600
	v_lshl_add_u32 v67, v23, 7, s0
	v_cndmask_b32_e32 v64, v64, v67, vcc
	v_add_u32_e32 v66, -20, v23
	v_cmp_gt_u32_e32 vcc, 8, v66
	s_nop 1
	s_mov_b32 s0, 0xd800000
	v_lshl_add_u32 v67, v66, 7, s0
	v_cndmask_b32_e32 v64, v64, v67, vcc
	v_add_u32_e32 v66, -28, v23
	v_cmp_gt_u32_e32 vcc, 4, v66
	s_nop 1
	s_mov_b32 s0, 0x6c00600
	v_lshl_add_u32 v67, v66, 7, s0
	v_cndmask_b32_e32 v64, v64, v67, vcc
	v_add_u32_e32 v64, v64, v65
	v_mov_b32_e32 v65, 0
	v_lshl_add_u64 v[2:3], s[50:51], 0, v[64:65]
	v_mov_b32_e32 v4, 0x1400
	v_add_u32_e32 v66, -20, v23
	v_cmp_gt_u32_e32 vcc, 8, v66
	s_nop 1
	v_mov_b32_e32 v67, 0x400
	v_cndmask_b32_e32 v4, v4, v67, vcc
	v_mov_b32_e32 v5, 0
	v_add_u32_e32 v66, -20, v23
	v_cmp_gt_u32_e32 vcc, 8, v66
	s_nop 1
	v_mov_b32_e32 v67, 0x800000
	v_cndmask_b32_e32 v5, v5, v67, vcc
	v_lshlrev_b32_e32 v63, 4, v59
	v_mov_b32_e32 v64, 0x9800000
	v_cmp_gt_u32_e32 vcc, 6, v23
	s_nop 1
	s_mov_b32 s0, 0x9800000
	v_lshl_add_u32 v67, v23, 7, s0
	v_cndmask_b32_e32 v64, v64, v67, vcc
	v_add_u32_e32 v66, -6, v23
	v_cmp_gt_u32_e32 vcc, 6, v66
	s_nop 1
	s_mov_b32 s0, 0x9e00000
	v_lshl_add_u32 v67, v66, 7, s0
	v_cndmask_b32_e32 v64, v64, v67, vcc
	v_add_u32_e32 v66, -18, v23
	v_cmp_gt_u32_e32 vcc, 6, v66
	s_nop 1
	s_mov_b32 s0, 0xaa00000
	v_lshl_add_u32 v67, v66, 7, s0
	v_cndmask_b32_e32 v64, v64, v67, vcc
	v_add_u32_e32 v66, -24, v23
	v_cmp_gt_u32_e32 vcc, 2, v66
	s_nop 1
	s_mov_b32 s0, 0xb000000
	v_lshl_add_u32 v67, v66, 7, s0
	v_cndmask_b32_e32 v64, v64, v67, vcc
	v_add_u32_e32 v64, v64, v63
	v_mov_b32_e32 v65, 0
	v_lshl_add_u64 v[14:15], s[50:51], 0, v[64:65]
	v_mov_b32_e32 v16, 0x300
	v_add_u32_e32 v66, -24, v23
	v_cmp_gt_u32_e32 vcc, 2, v66
	s_nop 1
	v_mov_b32_e32 v67, 0x100
	v_cndmask_b32_e32 v16, v16, v67, vcc
	v_lshlrev_b32_e32 v63, 5, v59
	v_mov_b32_e32 v64, 0x2000000
	v_add_u32_e32 v66, -6, v23
	v_cmp_gt_u32_e32 vcc, 6, v66
	s_nop 1
	s_mov_b32 s0, 0x2000000
	v_lshl_add_u32 v67, v66, 8, s0
	v_cndmask_b32_e32 v64, v64, v67, vcc
	v_add_u32_e32 v66, -12, v23
	v_cmp_gt_u32_e32 vcc, 6, v66
	s_nop 1
	s_mov_b32 s0, 0x2c00000
	v_lshl_add_u32 v67, v66, 8, s0
	v_cndmask_b32_e32 v64, v64, v67, vcc
	v_add_u32_e32 v66, -24, v23
	v_cmp_gt_u32_e32 vcc, 2, v66
	s_nop 1
	s_mov_b32 s0, 0x3800000
	v_lshl_add_u32 v67, v66, 8, s0
	v_cndmask_b32_e32 v64, v64, v67, vcc
	v_add_u32_e32 v66, -26, v23
	v_cmp_gt_u32_e32 vcc, 2, v66
	s_nop 1
	s_mov_b32 s0, 0x3c00000
	v_lshl_add_u32 v67, v66, 8, s0
	v_cndmask_b32_e32 v64, v64, v67, vcc
	v_add_u32_e32 v64, v64, v63
	v_mov_b32_e32 v65, 0
	v_lshl_add_u64 v[18:19], s[48:49], 0, v[64:65]
	v_mov_b32_e32 v20, 0x600
	v_add_u32_e32 v66, -24, v23
	v_cmp_gt_u32_e32 vcc, 4, v66
	s_nop 1
	v_mov_b32_e32 v67, 0x200
	v_cndmask_b32_e32 v20, v20, v67, vcc
	s_waitcnt lgkmcnt(0)
	s_lshl_b32 s0, s5, 8
	s_add_u32 s24, s24, s0
	s_addc_u32 s25, s25, 0
	s_add_u32 s26, s26, s0
	s_addc_u32 s27, s27, 0
	s_add_u32 s28, s28, s0
	s_addc_u32 s29, s29, 0
	s_add_u32 s30, s30, s0
	s_addc_u32 s31, s31, 0
	v_mov_b32_e32 v60, s24
	v_mov_b32_e32 v61, s25
	v_add_u32_e32 v66, -6, v23
	v_cmp_gt_u32_e32 vcc, 6, v66
	s_nop 1
	v_mov_b32_e32 v66, s26
	v_mov_b32_e32 v67, s27
	v_cndmask_b32_e32 v60, v60, v66, vcc
	v_cndmask_b32_e32 v61, v61, v67, vcc
	v_add_u32_e32 v66, -18, v23
	v_cmp_gt_u32_e32 vcc, 6, v66
	s_nop 1
	v_mov_b32_e32 v66, s28
	v_mov_b32_e32 v67, s29
	v_cndmask_b32_e32 v60, v60, v66, vcc
	v_cndmask_b32_e32 v61, v61, v67, vcc
	v_add_u32_e32 v66, -24, v23
	v_cmp_gt_u32_e32 vcc, 2, v66
	s_nop 1
	v_mov_b32_e32 v66, s30
	v_mov_b32_e32 v67, s31
	v_cndmask_b32_e32 v60, v60, v66, vcc
	v_cndmask_b32_e32 v61, v61, v67, vcc
	v_lshlrev_b32_e32 v64, 5, v59
	v_mov_b32_e32 v65, 0
	v_lshl_add_u64 v[60:61], v[60:61], 0, v[64:65]
	global_load_dwordx4 v[6:9], v[60:61], off
	global_load_dwordx4 v[10:13], v[60:61], off offset:16
	s_add_u32 s18, s50, 0x5080000
	s_addc_u32 s19, s51, 0
	s_waitcnt vmcnt(0)
	v_mad_u64_u32 v[56:57], s[26:27], s3, v4, v[2:3]
	v_mov_b32_e32 v66, 0
	v_add_co_u32_e32 v60, vcc, v56, v5
	s_nop 1
	v_addc_co_u32_e32 v61, vcc, v57, v66, vcc
	global_load_dwordx4 v[28:31], v[60:61], off
	global_load_dwordx4 v[24:27], v[56:57], off
	s_waitcnt vmcnt(0)
	s_cmpk_lt_u32 s3, 0x1000
	s_cbranch_scc0 .Lpa_ctx_done
	s_branch .Lpa_ctx_body
.Lpa_ctx_top:
	s_waitcnt vmcnt(3)
.Lpa_ctx_body:
	v_lshlrev_b32_e32 v32, 16, v24
	v_and_b32_e32 v33, s85, v24
	v_lshlrev_b32_e32 v34, 16, v25
	v_and_b32_e32 v35, s85, v25
	v_lshlrev_b32_e32 v36, 16, v26
	v_and_b32_e32 v37, s85, v26
	v_lshlrev_b32_e32 v38, 16, v27
	v_and_b32_e32 v39, s85, v27
	s_mov_b64 exec, s[6:7]
	v_lshlrev_b32_e32 v66, 16, v28
	v_and_b32_e32 v67, s85, v28
	v_add_f32_e32 v32, v32, v66
	v_add_f32_e32 v33, v33, v67
	v_lshlrev_b32_e32 v66, 16, v29
	v_and_b32_e32 v67, s85, v29
	v_add_f32_e32 v34, v34, v66
	v_add_f32_e32 v35, v35, v67
	v_lshlrev_b32_e32 v66, 16, v30
	v_and_b32_e32 v67, s85, v30
	v_add_f32_e32 v36, v36, v66
	v_add_f32_e32 v37, v37, v67
	v_lshlrev_b32_e32 v66, 16, v31
	v_and_b32_e32 v67, s85, v31
	v_add_f32_e32 v38, v38, v66
	v_add_f32_e32 v39, v39, v67
	s_mov_b64 exec, -1
	s_add_i32 s17, s3, s4
	s_min_u32 s17, s17, 0x1fff
	v_mad_u64_u32 v[56:57], s[26:27], s17, v4, v[2:3]
	v_mov_b32_e32 v66, 0
	v_add_co_u32_e32 v60, vcc, v56, v5
	s_nop 1
	v_addc_co_u32_e32 v61, vcc, v57, v66, vcc
	global_load_dwordx4 v[28:31], v[60:61], off
	global_load_dwordx4 v[24:27], v[56:57], off
	v_mul_f32_e32 v66, v32, v32
	v_fmac_f32_e32 v66, v33, v33
	v_fmac_f32_e32 v66, v34, v34
	v_fmac_f32_e32 v66, v35, v35
	v_fmac_f32_e32 v66, v36, v36
	v_fmac_f32_e32 v66, v37, v37
	v_fmac_f32_e32 v66, v38, v38
	v_fmac_f32_e32 v66, v39, v39
	s_nop 1
	v_add_f32_dpp v66, v66, v66 quad_perm:[1,0,3,2] row_mask:0xf bank_mask:0xf
	s_nop 1
	v_add_f32_dpp v66, v66, v66 quad_perm:[2,3,0,1] row_mask:0xf bank_mask:0xf
	s_nop 1
	v_add_f32_dpp v66, v66, v66 row_half_mirror row_mask:0xf bank_mask:0xf
	v_mov_b32_e32 v67, 0x358637bd
	v_fmac_f32_e32 v67, s16, v66
	v_rsq_f32_e32 v67, v67
	s_mov_b64 exec, s[8:9]
	v_mul_f32_e32 v32, v32, v67
	v_mul_f32_e32 v33, v33, v67
	v_mul_f32_e32 v34, v34, v67
	v_mul_f32_e32 v35, v35, v67
	v_mul_f32_e32 v36, v36, v67
	v_mul_f32_e32 v37, v37, v67
	v_mul_f32_e32 v38, v38, v67
	v_mul_f32_e32 v39, v39, v67
	v_mul_f32_e32 v32, v32, v6
	v_mul_f32_e32 v33, v33, v7
	v_mul_f32_e32 v34, v34, v8
	v_mul_f32_e32 v35, v35, v9
	v_mul_f32_e32 v36, v36, v10
	v_mul_f32_e32 v37, v37, v11
	v_mul_f32_e32 v38, v38, v12
	v_mul_f32_e32 v39, v39, v13
	s_mov_b64 exec, -1
	s_lshr_b32 s22, s3, 8
	s_lshl_b32 s22, s22, 1
	s_add_i32 s22, s22, s5
	s_lshl_b32 s22, s22, 8
	s_and_b32 s0, s3, 0xff
	s_add_i32 s22, s22, s0
	v_mad_u64_u32 v[60:61], s[26:27], s22, v20, v[18:19]
	s_mov_b64 exec, s[10:11]
	global_store_dwordx4 v[60:61], v[32:35], off
	global_store_dwordx4 v[60:61], v[36:39], off offset:16
	s_mov_b64 exec, -1
	v_mul_f32_e32 v32, v32, v17
	v_mul_f32_e32 v33, v33, v17
	v_mul_f32_e32 v34, v34, v17
	v_mul_f32_e32 v35, v35, v17
	v_mul_f32_e32 v36, v36, v17
	v_mul_f32_e32 v37, v37, v17
	v_mul_f32_e32 v38, v38, v17
	v_mul_f32_e32 v39, v39, v17
	v_cvt_pk_bf16_f32 v62, v32, v33
	v_cvt_pk_bf16_f32 v63, v34, v35
	v_cvt_pk_bf16_f32 v64, v36, v37
	v_cvt_pk_bf16_f32 v65, v38, v39
	v_mad_u64_u32 v[56:57], s[26:27], s3, v16, v[14:15]
	s_mov_b64 exec, s[12:13]
	global_store_dwordx4 v[56:57], v[62:65], off
	s_mov_b64 exec, -1
	s_add_i32 s3, s3, s4
	s_cmpk_lt_u32 s3, 0x1000
	s_cbranch_scc1 .Lpa_ctx_top
.Lpa_ctx_done:
	s_cmpk_lt_u32 s3, 0x2000
	s_cbranch_scc0 .Lpa_done
	s_and_b32 s0, s3, 0x7ff
	s_lshl_b32 s0, s0, 8
	s_add_u32 s20, s18, s0
	s_addc_u32 s21, s19, 0
	global_load_dwordx4 v[40:43], v21, s[20:21]
	global_load_dwordx4 v[44:47], v21, s[20:21] offset:16
	global_load_dwordx4 v[48:51], v21, s[20:21] offset:32
	global_load_dwordx4 v[52:55], v21, s[20:21] offset:48
	s_waitcnt vmcnt(0)
	s_branch .Lpa_lat_body
.Lpa_lat_top:
	s_waitcnt vmcnt(5)
.Lpa_lat_body:
	v_lshlrev_b32_e32 v32, 16, v24
	v_and_b32_e32 v33, s85, v24
	v_lshlrev_b32_e32 v34, 16, v25
	v_and_b32_e32 v35, s85, v25
	v_lshlrev_b32_e32 v36, 16, v26
	v_and_b32_e32 v37, s85, v26
	v_lshlrev_b32_e32 v38, 16, v27
	v_and_b32_e32 v39, s85, v27
	s_mov_b64 exec, s[6:7]
	v_lshlrev_b32_e32 v66, 16, v28
	v_and_b32_e32 v67, s85, v28
	v_add_f32_e32 v32, v32, v66
	v_add_f32_e32 v33, v33, v67
	v_lshlrev_b32_e32 v66, 16, v29
	v_and_b32_e32 v67, s85, v29
	v_add_f32_e32 v34, v34, v66
	v_add_f32_e32 v35, v35, v67
	v_lshlrev_b32_e32 v66, 16, v30
	v_and_b32_e32 v67, s85, v30
	v_add_f32_e32 v36, v36, v66
	v_add_f32_e32 v37, v37, v67
	v_lshlrev_b32_e32 v66, 16, v31
	v_and_b32_e32 v67, s85, v31
	v_add_f32_e32 v38, v38, v66
	v_add_f32_e32 v39, v39, v67
	s_mov_b64 exec, -1
	s_add_i32 s17, s3, s4
	s_min_u32 s17, s17, 0x1fff
	v_mad_u64_u32 v[56:57], s[26:27], s17, v4, v[2:3]
	v_mov_b32_e32 v66, 0
	v_add_co_u32_e32 v60, vcc, v56, v5
	s_nop 1
	v_addc_co_u32_e32 v61, vcc, v57, v66, vcc
	global_load_dwordx4 v[28:31], v[60:61], off
	global_load_dwordx4 v[24:27], v[56:57], off
	v_mul_f32_e32 v66, v32, v32
	v_fmac_f32_e32 v66, v33, v33
	v_fmac_f32_e32 v66, v34, v34
	v_fmac_f32_e32 v66, v35, v35
	v_fmac_f32_e32 v66, v36, v36
	v_fmac_f32_e32 v66, v37, v37
	v_fmac_f32_e32 v66, v38, v38
	v_fmac_f32_e32 v66, v39, v39
	s_nop 1
	v_add_f32_dpp v66, v66, v66 quad_perm:[1,0,3,2] row_mask:0xf bank_mask:0xf
	s_nop 1
	v_add_f32_dpp v66, v66, v66 quad_perm:[2,3,0,1] row_mask:0xf bank_mask:0xf
	s_nop 1
	v_add_f32_dpp v66, v66, v66 row_half_mirror row_mask:0xf bank_mask:0xf
	v_mov_b32_e32 v67, 0x358637bd
	v_fmac_f32_e32 v67, s16, v66
	v_rsq_f32_e32 v67, v67
	s_mov_b64 exec, s[8:9]
	v_mul_f32_e32 v32, v32, v67
	v_mul_f32_e32 v33, v33, v67
	v_mul_f32_e32 v34, v34, v67
	v_mul_f32_e32 v35, v35, v67
	v_mul_f32_e32 v36, v36, v67
	v_mul_f32_e32 v37, v37, v67
	v_mul_f32_e32 v38, v38, v67
	v_mul_f32_e32 v39, v39, v67
	v_mul_f32_e32 v32, v32, v6
	v_mul_f32_e32 v33, v33, v7
	v_mul_f32_e32 v34, v34, v8
	v_mul_f32_e32 v35, v35, v9
	v_mul_f32_e32 v36, v36, v10
	v_mul_f32_e32 v37, v37, v11
	v_mul_f32_e32 v38, v38, v12
	v_mul_f32_e32 v39, v39, v13
	s_mov_b64 exec, -1
	s_waitcnt vmcnt(3)
	s_mov_b64 exec, s[14:15]
	s_cbranch_execz .Lpa_norope
	v_xor_b32_e32 v41, v22, v41
	v_xor_b32_e32 v43, v22, v43
	v_xor_b32_e32 v45, v22, v45
	v_xor_b32_e32 v47, v22, v47
	v_xor_b32_e32 v49, v22, v49
	v_xor_b32_e32 v51, v22, v51
	v_xor_b32_e32 v53, v22, v53
	v_xor_b32_e32 v55, v22, v55
	v_mov_b32_dpp v66, v32 quad_perm:[2,3,0,1] row_mask:0xf bank_mask:0xf
	v_mul_f32_e32 v32, v32, v40
	s_nop 0
	v_fmac_f32_e32 v32, v66, v41
	v_mov_b32_dpp v66, v33 quad_perm:[2,3,0,1] row_mask:0xf bank_mask:0xf
	v_mul_f32_e32 v33, v33, v42
	s_nop 0
	v_fmac_f32_e32 v33, v66, v43
	v_mov_b32_dpp v66, v34 quad_perm:[2,3,0,1] row_mask:0xf bank_mask:0xf
	v_mul_f32_e32 v34, v34, v44
	s_nop 0
	v_fmac_f32_e32 v34, v66, v45
	v_mov_b32_dpp v66, v35 quad_perm:[2,3,0,1] row_mask:0xf bank_mask:0xf
	v_mul_f32_e32 v35, v35, v46
	s_nop 0
	v_fmac_f32_e32 v35, v66, v47
	v_mov_b32_dpp v66, v36 quad_perm:[2,3,0,1] row_mask:0xf bank_mask:0xf
	v_mul_f32_e32 v36, v36, v48
	s_nop 0
	v_fmac_f32_e32 v36, v66, v49
	v_mov_b32_dpp v66, v37 quad_perm:[2,3,0,1] row_mask:0xf bank_mask:0xf
	v_mul_f32_e32 v37, v37, v50
	s_nop 0
	v_fmac_f32_e32 v37, v66, v51
	v_mov_b32_dpp v66, v38 quad_perm:[2,3,0,1] row_mask:0xf bank_mask:0xf
	v_mul_f32_e32 v38, v38, v52
	s_nop 0
	v_fmac_f32_e32 v38, v66, v53
	v_mov_b32_dpp v66, v39 quad_perm:[2,3,0,1] row_mask:0xf bank_mask:0xf
	v_mul_f32_e32 v39, v39, v54
	s_nop 0
	v_fmac_f32_e32 v39, v66, v55
.Lpa_norope:
	s_mov_b64 exec, -1
	s_add_i32 s17, s3, s4
	s_min_u32 s17, s17, 0x1fff
	s_and_b32 s0, s17, 0x7ff
	s_lshl_b32 s0, s0, 8
	s_add_u32 s20, s18, s0
	s_addc_u32 s21, s19, 0
	global_load_dwordx4 v[40:43], v21, s[20:21]
	global_load_dwordx4 v[44:47], v21, s[20:21] offset:16
	global_load_dwordx4 v[48:51], v21, s[20:21] offset:32
	global_load_dwordx4 v[52:55], v21, s[20:21] offset:48
	v_mul_f32_e32 v32, v32, v17
	v_mul_f32_e32 v33, v33, v17
	v_mul_f32_e32 v34, v34, v17
	v_mul_f32_e32 v35, v35, v17
	v_mul_f32_e32 v36, v36, v17
	v_mul_f32_e32 v37, v37, v17
	v_mul_f32_e32 v38, v38, v17
	v_mul_f32_e32 v39, v39, v17
	v_cvt_pk_bf16_f32 v62, v32, v33
	v_cvt_pk_bf16_f32 v63, v34, v35
	v_cvt_pk_bf16_f32 v64, v36, v37
	v_cvt_pk_bf16_f32 v65, v38, v39
	v_mad_u64_u32 v[56:57], s[26:27], s3, v16, v[14:15]
	s_mov_b64 exec, s[12:13]
	global_store_dwordx4 v[56:57], v[62:65], off
	s_mov_b64 exec, -1
	s_add_i32 s3, s3, s4
	s_cmpk_lt_u32 s3, 0x2000
	s_cbranch_scc1 .Lpa_lat_top
.Lpa_done:
	s_waitcnt vmcnt(1)
	s_mov_b32 s56, 0x800000
